# group barriers incl. w_in->post site, L1 invalidate issued at arrival in the group barrier; norm/post/final row remap; GEMM loop edits
# speedup vs baseline: 1.0108x; 1.0032x over previous
.LBB0_284:
	v_readlane_b32 s4, v255, 15
	s_add_i32 s34, s4, 1
	v_readlane_b32 s4, v255, 0
	v_readlane_b32 s5, v255, 1
	s_cmp_ge_i32 s34, s5
	s_cbranch_scc1 .LBB0_338
	s_bitcmp0_b32 s32, 0
	s_cbranch_scc1 .Lgb0_slow
	s_waitcnt vmcnt(0)
	s_barrier
	s_add_i32 s32, s32, 16
	v_cmp_eq_u32_e32 vcc, 0, v0
	s_and_saveexec_b64 s[4:5], vcc
	s_cbranch_execz .Lgb0_join
	s_load_dwordx2 s[8:9], s[0:1], 0xd8
	s_and_b32 s11, s87, 63
	s_lshl_b32 s11, s11, 8
	v_mov_b32_e32 v248, 0
	v_mov_b32_e32 v249, 1
	s_mov_b32 s10, 0
	s_waitcnt lgkmcnt(0)
	s_add_u32 s8, s8, s11
	s_addc_u32 s9, s9, 0
	s_add_u32 s8, s8, 0x10000
	s_addc_u32 s9, s9, 0
	global_atomic_add v248, v249, s[8:9]
	buffer_inv sc1

.Lgb0_done:
.Lgb0_join:
	s_or_b64 exec, exec, s[4:5]
	s_barrier
	s_branch .LBB0_338

.LBB0_359:
	v_readlane_b32 s4, v255, 15
	s_add_i32 s34, s4, 2
	v_readlane_b32 s4, v255, 0
	v_readlane_b32 s5, v255, 1
	s_cmp_ge_i32 s34, s5
	s_cbranch_scc1 .LBB0_413
	s_bitcmp0_b32 s32, 0
	s_cbranch_scc1 .Lgb1_slow
	s_waitcnt vmcnt(0)
	s_barrier
	s_add_i32 s32, s32, 16
	v_cmp_eq_u32_e32 vcc, 0, v0
	s_and_saveexec_b64 s[4:5], vcc
	s_cbranch_execz .Lgb1_join
	s_load_dwordx2 s[8:9], s[0:1], 0xd8
	s_and_b32 s11, s87, 63
	s_lshl_b32 s11, s11, 8
	v_mov_b32_e32 v248, 0
	v_mov_b32_e32 v249, 1
	s_mov_b32 s10, 0
	s_waitcnt lgkmcnt(0)
	s_add_u32 s8, s8, s11
	s_addc_u32 s9, s9, 0
	s_add_u32 s8, s8, 0x10000
	s_addc_u32 s9, s9, 0
	global_atomic_add v248, v249, s[8:9]
	buffer_inv sc1

.LBB0_442:
	v_readlane_b32 s4, v255, 15
	s_add_i32 s34, s4, 3
	v_readlane_b32 s4, v255, 0
	v_readlane_b32 s5, v255, 1
	s_cmp_ge_i32 s34, s5
	s_cbranch_scc1 .LBB0_496
	s_bitcmp0_b32 s32, 0
	s_cbranch_scc1 .Lgb2_slow
	s_cmp_eq_u32 s34, 25
	s_cbranch_scc1 .Lgb2_slow
	s_waitcnt vmcnt(0)
	s_barrier
	s_add_i32 s32, s32, 16
	v_cmp_eq_u32_e32 vcc, 0, v0
	s_and_saveexec_b64 s[4:5], vcc
	s_cbranch_execz .Lgb2_join
	s_load_dwordx2 s[8:9], s[0:1], 0xd8
	s_and_b32 s11, s87, 63
	s_lshl_b32 s11, s11, 8
	v_mov_b32_e32 v248, 0
	v_mov_b32_e32 v249, 1
	s_mov_b32 s10, 0
	s_waitcnt lgkmcnt(0)
	s_add_u32 s8, s8, s11
	s_addc_u32 s9, s9, 0
	s_add_u32 s8, s8, 0x10000
	s_addc_u32 s9, s9, 0
	global_atomic_add v248, v249, s[8:9]
	buffer_inv sc1

.LBB0_725:
	v_readlane_b32 s4, v255, 15
	s_add_i32 s17, s4, 5
	v_readlane_b32 s4, v255, 0
	v_readlane_b32 s5, v255, 1
	s_cmp_ge_i32 s17, s5
	s_waitcnt vmcnt(0)
	s_barrier
	s_cbranch_scc1 .LBB0_779
	s_bitcmp0_b32 s32, 0
	s_cbranch_scc1 .Lgb4_slow
	s_waitcnt vmcnt(0)
	s_barrier
	s_add_i32 s32, s32, 16
	v_cmp_eq_u32_e32 vcc, 0, v0
	s_and_saveexec_b64 s[4:5], vcc
	s_cbranch_execz .Lgb4_join
	s_load_dwordx2 s[8:9], s[0:1], 0xd8
	s_and_b32 s11, s87, 63
	s_lshl_b32 s11, s11, 8
	v_mov_b32_e32 v248, 0
	v_mov_b32_e32 v249, 1
	s_mov_b32 s10, 0
	s_waitcnt lgkmcnt(0)
	s_add_u32 s8, s8, s11
	s_addc_u32 s9, s9, 0
	s_add_u32 s8, s8, 0x10000
	s_addc_u32 s9, s9, 0
	global_atomic_add v248, v249, s[8:9]
	buffer_inv sc1

.Lgb4_slow:
	s_mov_b64 s[6:7], s[0:1]
	s_mov_b32 s34, s90
	s_waitcnt vmcnt(0)
	s_barrier
	s_mov_b64 s[4:5], exec
	v_readlane_b32 s8, v255, 5
	v_readlane_b32 s9, v255, 6
	s_and_b64 s[8:9], s[4:5], s[8:9]
	s_mov_b64 exec, s[8:9]
	s_cbranch_execz .LBB0_778
	v_readlane_b32 s8, v255, 16
	s_load_dwordx2 s[6:7], s[6:7], 0xd8
	s_waitcnt vmcnt(0) expcnt(0) lgkmcnt(0)
	v_mov_b32_e32 v2, s8
	ds_read_b32 v5, v2
	v_readlane_b32 s8, v255, 17
	s_waitcnt lgkmcnt(0)
	v_cmp_ne_u32_e32 vcc, 0, v5
	v_mov_b32_e32 v2, s8
	ds_read_b32 v4, v2
	s_cbranch_vccnz .LBB0_742
	v_readlane_b32 s8, v255, 2
	v_readlane_b32 s9, v255, 3
	s_load_dwordx2 s[14:15], s[8:9], 0x4
	s_add_u32 s8, s6, 0x4200
	s_addc_u32 s9, s7, 0
	s_add_u32 s10, s6, 0x4400
	s_addc_u32 s11, s7, 0
	s_waitcnt lgkmcnt(0)
	s_mul_i32 s35, s14, s65
	s_add_u32 s14, s6, 0x4500
	s_mul_i32 s35, s35, s15
	s_addc_u32 s15, s7, 0
	s_add_u32 s18, s6, 0x4600
	s_addc_u32 s19, s7, 0
	s_add_u32 s20, s6, 0x4700
	s_addc_u32 s21, s7, 0
	s_add_u32 s22, s6, 0x4800
	s_addc_u32 s23, s7, 0
	s_add_u32 s24, s6, 0x4900
	s_addc_u32 s25, s7, 0
	s_add_u32 s26, s6, 0x4a00
	s_addc_u32 s27, s7, 0
	s_add_u32 s28, s6, 0x4b00
	s_addc_u32 s29, s7, 0
	s_add_u32 s30, s6, 0x4c00
	s_addc_u32 s31, s7, 0
	s_add_u32 s36, s6, 0x4d00
	s_addc_u32 s37, s7, 0
	s_add_u32 s44, s6, 0x4e00
	s_addc_u32 s45, s7, 0
	s_add_u32 s46, s6, 0x4f00
	s_addc_u32 s47, s7, 0
	s_add_u32 s72, s6, 0x5000
	s_addc_u32 s73, s7, 0
	s_add_u32 s74, s6, 0x5100
	s_addc_u32 s75, s7, 0
	s_add_u32 s76, s6, 0x5200
	s_addc_u32 s77, s7, 0
	s_add_u32 s78, s6, 0x5300
	s_addc_u32 s79, s7, 0
	s_mov_b32 s40, 1
	s_branch .LBB0_730

.LBB0_1221:
	s_bitcmp0_b32 s32, 0
	s_cbranch_scc1 .Lgb3_slow
	s_waitcnt vmcnt(0)
	s_barrier
	s_add_i32 s32, s32, 16
	v_cmp_eq_u32_e32 vcc, 0, v0
	s_and_saveexec_b64 s[4:5], vcc
	s_cbranch_execz .Lgb3_join
	s_load_dwordx2 s[8:9], s[0:1], 0xd8
	s_and_b32 s11, s87, 63
	s_lshl_b32 s11, s11, 8
	v_mov_b32_e32 v248, 0
	v_mov_b32_e32 v249, 1
	s_mov_b32 s10, 0
	s_waitcnt lgkmcnt(0)
	s_add_u32 s8, s8, s11
	s_addc_u32 s9, s9, 0
	s_add_u32 s8, s8, 0x10000
	s_addc_u32 s9, s9, 0
	global_atomic_add v248, v249, s[8:9]
	buffer_inv sc1
